# plus: accumulator zeroing with v_mov_b64 pairs in the six GEMM instances
# speedup vs baseline: 1.0115x; 1.0017x over previous
; template <class Epi, class Sched, bool ALIGN_EPI = false, bool SP2 = false>
; __device__ __forceinline__ void gemm_phase(PG8_LAS unsigned char* lds, const Gemm g, const Sched& S, const Epi& E, const int tid) {
;     ...
;     f32x4 acc[2][2][4][2];
; #pragma unroll
;     for (int a = 0; a < 2; ++a)
; #pragma unroll
;         for (int b = 0; b < 2; ++b)
; #pragma unroll
;             for (int m = 0; m < 4; ++m)
; #pragma unroll
;                 for (int n = 0; n < 2; ++n) acc[a][b][m][n] = (f32x4){0.f, 0.f, 0.f, 0.f};
;     ...
;         const bool has_next = S.next(ui + 1, nxt);
;         const char* nA = has_next ? (const char*)g.A + (size_t)nxt.pm * tstepA : cA; const char* nB = has_next ? (const char*)g.Bt + (size_t)nxt.pn * tstepB : cB;
;         for (int t = 0; t < nt; t += 2) {
;             const bool last = (t == nt - 2);
;             const char* a1 = cA + (size_t)(t + 1) * kstep;
;             const char* a2 = last ? nA : cA + (size_t)(t + 2) * kstep; const char* b2 = last ? nB : cB + (size_t)(t + 2) * kstep;
;             const char* a3 = a2 + kstep; const char* b3 = b2 + kstep;
.LBB0_35:
	s_ashr_i32 s19, s18, 31
	s_lshl_b64 s[24:25], s[18:19], 19
	s_add_u32 s38, s2, s24
	s_addc_u32 s39, s4, s25
	s_and_b64 s[24:25], s[36:37], exec
	s_cselect_b32 s19, s39, s49
	s_cselect_b32 s53, s38, s48
	s_ashr_i32 s15, s14, 31
	s_lshl_b64 s[24:25], s[14:15], 19
	s_add_u32 s42, s17, s24
	s_addc_u32 s43, s20, s25
	s_and_b64 s[24:25], s[36:37], exec
	s_cselect_b32 s15, s43, s47
	s_cselect_b32 s54, s42, s46
	s_add_u32 s55, s46, 0x100
	s_addc_u32 s58, s47, 0
	s_add_u32 s46, s48, 0x40080
	v_mov_b32_e32 v0, 0
	s_addc_u32 s47, s49, 0
	s_mov_b32 s59, -2
	v_mov_b32_e32 v1, v0
	v_mov_b64_e32 v[2:3], 0
	v_mov_b64_e32 v[4:5], 0
	v_mov_b64_e32 v[6:7], 0
	v_mov_b64_e32 v[8:9], 0
	v_mov_b64_e32 v[10:11], 0
	v_mov_b64_e32 v[12:13], 0
	v_mov_b64_e32 v[14:15], 0
	v_mov_b64_e32 v[16:17], 0
	v_mov_b64_e32 v[18:19], 0
	v_mov_b64_e32 v[20:21], 0
	v_mov_b64_e32 v[22:23], 0
	v_mov_b64_e32 v[24:25], 0
	v_mov_b64_e32 v[26:27], 0
	v_mov_b64_e32 v[28:29], 0
	v_mov_b64_e32 v[30:31], 0
	v_mov_b64_e32 v[32:33], 0
	v_mov_b64_e32 v[34:35], 0
	v_mov_b64_e32 v[36:37], 0
	v_mov_b64_e32 v[38:39], 0
	v_mov_b64_e32 v[40:41], 0
	v_mov_b64_e32 v[42:43], 0
	v_mov_b64_e32 v[44:45], 0
	v_mov_b64_e32 v[46:47], 0
	v_mov_b64_e32 v[48:49], 0
	v_mov_b64_e32 v[50:51], 0
	v_mov_b64_e32 v[52:53], 0
	v_mov_b64_e32 v[54:55], 0
	v_mov_b64_e32 v[56:57], 0
	v_mov_b64_e32 v[58:59], 0
	v_mov_b64_e32 v[60:61], 0
	v_mov_b64_e32 v[62:63], 0
	v_mov_b64_e32 v[64:65], 0
	v_mov_b64_e32 v[66:67], 0
	v_mov_b64_e32 v[68:69], 0
	v_mov_b64_e32 v[70:71], 0
	v_mov_b64_e32 v[72:73], 0
	v_mov_b64_e32 v[74:75], 0
	v_mov_b64_e32 v[76:77], 0
	v_mov_b64_e32 v[78:79], 0
	v_mov_b64_e32 v[80:81], 0
	v_mov_b64_e32 v[82:83], 0
	v_mov_b64_e32 v[84:85], 0
	v_mov_b64_e32 v[86:87], 0
	v_mov_b64_e32 v[88:89], 0
	v_mov_b64_e32 v[90:91], 0
	v_mov_b64_e32 v[92:93], 0
	v_mov_b64_e32 v[94:95], 0
	v_mov_b64_e32 v[96:97], 0
	v_mov_b64_e32 v[98:99], 0
	v_mov_b64_e32 v[100:101], 0
	v_mov_b64_e32 v[102:103], 0
	v_mov_b64_e32 v[104:105], 0
	v_mov_b64_e32 v[106:107], 0
	v_mov_b64_e32 v[108:109], 0
	v_mov_b64_e32 v[110:111], 0
	v_mov_b64_e32 v[112:113], 0
	v_mov_b64_e32 v[114:115], 0
	v_mov_b64_e32 v[116:117], 0
	v_mov_b64_e32 v[118:119], 0
	v_mov_b64_e32 v[120:121], 0
	v_mov_b64_e32 v[122:123], 0
	v_mov_b64_e32 v[124:125], 0
	v_mov_b64_e32 v[126:127], 0

; template <class Epi, class Sched, bool ALIGN_EPI = false, bool SP2 = false>
; __device__ __forceinline__ void gemm_phase(PG8_LAS unsigned char* lds, const Gemm g, const Sched& S, const Epi& E, const int tid) {
;     ...
;     f32x4 acc[2][2][4][2];
; #pragma unroll
;     for (int a = 0; a < 2; ++a)
; #pragma unroll
;         for (int b = 0; b < 2; ++b)
; #pragma unroll
;             for (int m = 0; m < 4; ++m)
; #pragma unroll
;                 for (int n = 0; n < 2; ++n) acc[a][b][m][n] = (f32x4){0.f, 0.f, 0.f, 0.f};
;     ...
;         const bool has_next = S.next(ui + 1, nxt);
;         const char* nA = has_next ? (const char*)g.A + (size_t)nxt.pm * tstepA : cA; const char* nB = has_next ? (const char*)g.Bt + (size_t)nxt.pn * tstepB : cB;
;         for (int t = 0; t < nt; t += 2) {
;             const bool last = (t == nt - 2);
;             const char* a1 = cA + (size_t)(t + 1) * kstep;
;             const char* a2 = last ? nA : cA + (size_t)(t + 2) * kstep; const char* b2 = last ? nB : cB + (size_t)(t + 2) * kstep;
;             const char* a3 = a2 + kstep; const char* b3 = b2 + kstep;
.LBB0_69:
	s_ashr_i32 s19, s18, 31
	s_lshl_b64 s[24:25], s[18:19], 19
	s_add_u32 s44, s14, s24
	s_addc_u32 s45, s15, s25
	s_and_b64 s[24:25], s[42:43], exec
	s_cselect_b32 s19, s45, s53
	s_cselect_b32 s63, s44, s52
	s_ashr_i32 s13, s12, 31
	s_lshl_b64 s[24:25], s[12:13], 19
	s_add_u32 s46, s16, s24
	s_addc_u32 s47, s17, s25
	s_and_b64 s[24:25], s[42:43], exec
	s_cselect_b32 s13, s47, s51
	s_cselect_b32 s65, s46, s50
	s_add_u32 s78, s50, 0x100
	s_addc_u32 s2, s51, 0
	s_add_u32 s50, s52, 0x40080
	v_mov_b32_e32 v0, 0
	s_addc_u32 s51, s53, 0
	s_mov_b32 s74, -2
	v_mov_b32_e32 v1, v0
	v_mov_b64_e32 v[2:3], 0
	v_mov_b64_e32 v[4:5], 0
	v_mov_b64_e32 v[6:7], 0
	v_mov_b64_e32 v[8:9], 0
	v_mov_b64_e32 v[10:11], 0
	v_mov_b64_e32 v[12:13], 0
	v_mov_b64_e32 v[14:15], 0
	v_mov_b64_e32 v[16:17], 0
	v_mov_b64_e32 v[18:19], 0
	v_mov_b64_e32 v[20:21], 0
	v_mov_b64_e32 v[22:23], 0
	v_mov_b64_e32 v[24:25], 0
	v_mov_b64_e32 v[26:27], 0
	v_mov_b64_e32 v[28:29], 0
	v_mov_b64_e32 v[30:31], 0
	v_mov_b64_e32 v[32:33], 0
	v_mov_b64_e32 v[34:35], 0
	v_mov_b64_e32 v[36:37], 0
	v_mov_b64_e32 v[38:39], 0
	v_mov_b64_e32 v[40:41], 0
	v_mov_b64_e32 v[42:43], 0
	v_mov_b64_e32 v[44:45], 0
	v_mov_b64_e32 v[46:47], 0
	v_mov_b64_e32 v[48:49], 0
	v_mov_b64_e32 v[50:51], 0
	v_mov_b64_e32 v[52:53], 0
	v_mov_b64_e32 v[54:55], 0
	v_mov_b64_e32 v[56:57], 0
	v_mov_b64_e32 v[58:59], 0
	v_mov_b64_e32 v[60:61], 0
	v_mov_b64_e32 v[62:63], 0
	v_mov_b64_e32 v[64:65], 0
	v_mov_b64_e32 v[66:67], 0
	v_mov_b64_e32 v[68:69], 0
	v_mov_b64_e32 v[70:71], 0
	v_mov_b64_e32 v[72:73], 0
	v_mov_b64_e32 v[74:75], 0
	v_mov_b64_e32 v[76:77], 0
	v_mov_b64_e32 v[78:79], 0
	v_mov_b64_e32 v[80:81], 0
	v_mov_b64_e32 v[82:83], 0
	v_mov_b64_e32 v[84:85], 0
	v_mov_b64_e32 v[86:87], 0
	v_mov_b64_e32 v[88:89], 0
	v_mov_b64_e32 v[90:91], 0
	v_mov_b64_e32 v[92:93], 0
	v_mov_b64_e32 v[94:95], 0
	v_mov_b64_e32 v[96:97], 0
	v_mov_b64_e32 v[98:99], 0
	v_mov_b64_e32 v[100:101], 0
	v_mov_b64_e32 v[102:103], 0
	v_mov_b64_e32 v[104:105], 0
	v_mov_b64_e32 v[106:107], 0
	v_mov_b64_e32 v[108:109], 0
	v_mov_b64_e32 v[110:111], 0
	v_mov_b64_e32 v[112:113], 0
	v_mov_b64_e32 v[114:115], 0
	v_mov_b64_e32 v[116:117], 0
	v_mov_b64_e32 v[118:119], 0
	v_mov_b64_e32 v[120:121], 0
	v_mov_b64_e32 v[122:123], 0
	v_mov_b64_e32 v[124:125], 0
	v_mov_b64_e32 v[126:127], 0

; template <class Epi, class Sched, bool ALIGN_EPI = false, bool SP2 = false>
; __device__ __forceinline__ void gemm_phase(PG8_LAS unsigned char* lds, const Gemm g, const Sched& S, const Epi& E, const int tid) {
;     ...
;     f32x4 acc[2][2][4][2];
; #pragma unroll
;     for (int a = 0; a < 2; ++a)
; #pragma unroll
;         for (int b = 0; b < 2; ++b)
; #pragma unroll
;             for (int m = 0; m < 4; ++m)
; #pragma unroll
;                 for (int n = 0; n < 2; ++n) acc[a][b][m][n] = (f32x4){0.f, 0.f, 0.f, 0.f};
;     ...
;         const bool has_next = S.next(ui + 1, nxt);
;         const char* nA = has_next ? (const char*)g.A + (size_t)nxt.pm * tstepA : cA; const char* nB = has_next ? (const char*)g.Bt + (size_t)nxt.pn * tstepB : cB;
;         for (int t = 0; t < nt; t += 2) {
;             const bool last = (t == nt - 2);
;             const char* a1 = cA + (size_t)(t + 1) * kstep;
;             const char* a2 = last ? nA : cA + (size_t)(t + 2) * kstep; const char* b2 = last ? nB : cB + (size_t)(t + 2) * kstep;
;             const char* a3 = a2 + kstep; const char* b3 = b2 + kstep;
.LBB0_89:
	s_ashr_i32 s55, s54, 31
	s_lshl_b64 s[24:25], s[54:55], 18
	s_add_u32 s82, s13, s24
	s_addc_u32 s83, s79, s25
	s_and_b64 s[24:25], s[80:81], exec
	s_cselect_b32 s55, s83, s87
	s_cselect_b32 vcc_lo, s82, s86
	s_ashr_i32 s53, s52, 31
	s_lshl_b64 s[24:25], s[52:53], 18
	s_add_u32 s84, s26, s24
	s_addc_u32 s85, s27, s25
	s_and_b64 s[24:25], s[80:81], exec
	s_cselect_b32 s53, s85, s7
	s_cselect_b32 vcc_hi, s84, s6
	s_add_u32 s2, s6, 0x100
	s_addc_u32 s74, s7, 0
	s_add_u32 s6, s86, 0x20080
	v_mov_b32_e32 v0, 0
	s_addc_u32 s7, s87, 0
	s_mov_b32 s24, -2
	v_mov_b32_e32 v1, v0
	v_mov_b64_e32 v[2:3], 0
	v_mov_b64_e32 v[4:5], 0
	v_mov_b64_e32 v[6:7], 0
	v_mov_b64_e32 v[8:9], 0
	v_mov_b64_e32 v[10:11], 0
	v_mov_b64_e32 v[12:13], 0
	v_mov_b64_e32 v[14:15], 0
	v_mov_b64_e32 v[16:17], 0
	v_mov_b64_e32 v[18:19], 0
	v_mov_b64_e32 v[20:21], 0
	v_mov_b64_e32 v[22:23], 0
	v_mov_b64_e32 v[24:25], 0
	v_mov_b64_e32 v[26:27], 0
	v_mov_b64_e32 v[28:29], 0
	v_mov_b64_e32 v[30:31], 0
	v_mov_b64_e32 v[32:33], 0
	v_mov_b64_e32 v[34:35], 0
	v_mov_b64_e32 v[36:37], 0
	v_mov_b64_e32 v[38:39], 0
	v_mov_b64_e32 v[40:41], 0
	v_mov_b64_e32 v[42:43], 0
	v_mov_b64_e32 v[44:45], 0
	v_mov_b64_e32 v[46:47], 0
	v_mov_b64_e32 v[48:49], 0
	v_mov_b64_e32 v[50:51], 0
	v_mov_b64_e32 v[52:53], 0
	v_mov_b64_e32 v[54:55], 0
	v_mov_b64_e32 v[56:57], 0
	v_mov_b64_e32 v[58:59], 0
	v_mov_b64_e32 v[60:61], 0
	v_mov_b64_e32 v[62:63], 0
	v_mov_b64_e32 v[68:69], 0
	v_mov_b64_e32 v[70:71], 0
	v_mov_b64_e32 v[72:73], 0
	v_mov_b64_e32 v[74:75], 0
	v_mov_b64_e32 v[84:85], 0
	v_mov_b64_e32 v[86:87], 0
	v_mov_b64_e32 v[88:89], 0
	v_mov_b64_e32 v[90:91], 0
	v_mov_b64_e32 v[96:97], 0
	v_mov_b64_e32 v[98:99], 0
	v_mov_b64_e32 v[100:101], 0
	v_mov_b64_e32 v[102:103], 0
	v_mov_b64_e32 v[108:109], 0
	v_mov_b64_e32 v[110:111], 0
	v_mov_b64_e32 v[112:113], 0
	v_mov_b64_e32 v[114:115], 0
	v_mov_b64_e32 v[120:121], 0
	v_mov_b64_e32 v[122:123], 0
	v_mov_b64_e32 v[124:125], 0
	v_mov_b64_e32 v[126:127], 0
	v_mov_b64_e32 v[136:137], 0
	v_mov_b64_e32 v[138:139], 0
	v_mov_b64_e32 v[140:141], 0
	v_mov_b64_e32 v[142:143], 0
	v_mov_b64_e32 v[144:145], 0
	v_mov_b64_e32 v[146:147], 0
	v_mov_b64_e32 v[148:149], 0
	v_mov_b64_e32 v[150:151], 0
	v_mov_b64_e32 v[152:153], 0
	v_mov_b64_e32 v[154:155], 0
	v_mov_b64_e32 v[156:157], 0
	v_mov_b64_e32 v[158:159], 0

; template <class Epi, class Sched, bool ALIGN_EPI = false, bool SP2 = false>
; __device__ __forceinline__ void gemm_phase(PG8_LAS unsigned char* lds, const Gemm g, const Sched& S, const Epi& E, const int tid) {
;     ...
;     f32x4 acc[2][2][4][2];
; #pragma unroll
;     for (int a = 0; a < 2; ++a)
; #pragma unroll
;         for (int b = 0; b < 2; ++b)
; #pragma unroll
;             for (int m = 0; m < 4; ++m)
; #pragma unroll
;                 for (int n = 0; n < 2; ++n) acc[a][b][m][n] = (f32x4){0.f, 0.f, 0.f, 0.f};
;     ...
;         const bool has_next = S.next(ui + 1, nxt);
;         const char* nA = has_next ? (const char*)g.A + (size_t)nxt.pm * tstepA : cA; const char* nB = has_next ? (const char*)g.Bt + (size_t)nxt.pn * tstepB : cB;
;         for (int t = 0; t < nt; t += 2) {
;             const bool last = (t == nt - 2);
;             const char* a1 = cA + (size_t)(t + 1) * kstep;
;             const char* a2 = last ? nA : cA + (size_t)(t + 2) * kstep; const char* b2 = last ? nB : cB + (size_t)(t + 2) * kstep;
;             const char* a3 = a2 + kstep; const char* b3 = b2 + kstep;
.LBB0_247:
	s_add_u32 s24, s50, 0x100
	v_mov_b32_e32 v0, 0
	s_addc_u32 s25, s51, 0
	s_mov_b32 s52, 0
	v_mov_b32_e32 v1, v0
	v_mov_b64_e32 v[2:3], 0
	v_mov_b64_e32 v[4:5], 0
	v_mov_b64_e32 v[6:7], 0
	v_mov_b64_e32 v[8:9], 0
	v_mov_b64_e32 v[10:11], 0
	v_mov_b64_e32 v[12:13], 0
	v_mov_b64_e32 v[14:15], 0
	v_mov_b64_e32 v[16:17], 0
	v_mov_b64_e32 v[18:19], 0
	v_mov_b64_e32 v[20:21], 0
	v_mov_b64_e32 v[22:23], 0
	v_mov_b64_e32 v[24:25], 0
	v_mov_b64_e32 v[26:27], 0
	v_mov_b64_e32 v[28:29], 0
	v_mov_b64_e32 v[30:31], 0
	v_mov_b64_e32 v[32:33], 0
	v_mov_b64_e32 v[34:35], 0
	v_mov_b64_e32 v[36:37], 0
	v_mov_b64_e32 v[38:39], 0
	v_mov_b64_e32 v[40:41], 0
	v_mov_b64_e32 v[42:43], 0
	v_mov_b64_e32 v[44:45], 0
	v_mov_b64_e32 v[46:47], 0
	v_mov_b64_e32 v[48:49], 0
	v_mov_b64_e32 v[50:51], 0
	v_mov_b64_e32 v[52:53], 0
	v_mov_b64_e32 v[54:55], 0
	v_mov_b64_e32 v[56:57], 0
	v_mov_b64_e32 v[58:59], 0
	v_mov_b64_e32 v[60:61], 0
	v_mov_b64_e32 v[62:63], 0
	v_mov_b64_e32 v[64:65], 0
	v_mov_b64_e32 v[66:67], 0
	v_mov_b64_e32 v[68:69], 0
	v_mov_b64_e32 v[70:71], 0
	v_mov_b64_e32 v[72:73], 0
	v_mov_b64_e32 v[74:75], 0
	v_mov_b64_e32 v[76:77], 0
	v_mov_b64_e32 v[78:79], 0
	v_mov_b64_e32 v[80:81], 0
	v_mov_b64_e32 v[82:83], 0
	v_mov_b64_e32 v[84:85], 0
	v_mov_b64_e32 v[86:87], 0
	v_mov_b64_e32 v[88:89], 0
	v_mov_b64_e32 v[90:91], 0
	v_mov_b64_e32 v[92:93], 0
	v_mov_b64_e32 v[94:95], 0
	v_mov_b64_e32 v[96:97], 0
	v_mov_b64_e32 v[98:99], 0
	v_mov_b64_e32 v[100:101], 0
	v_mov_b64_e32 v[102:103], 0
	v_mov_b64_e32 v[104:105], 0
	v_mov_b64_e32 v[106:107], 0
	v_mov_b64_e32 v[108:109], 0
	v_mov_b64_e32 v[110:111], 0
	v_mov_b64_e32 v[112:113], 0
	v_mov_b64_e32 v[114:115], 0
	v_mov_b64_e32 v[116:117], 0
	v_mov_b64_e32 v[118:119], 0
	v_mov_b64_e32 v[120:121], 0
	v_mov_b64_e32 v[122:123], 0
	v_mov_b64_e32 v[124:125], 0
	v_mov_b64_e32 v[126:127], 0

; template <class Epi, class Sched, bool ALIGN_EPI = false, bool SP2 = false>
; __device__ __forceinline__ void gemm_phase(PG8_LAS unsigned char* lds, const Gemm g, const Sched& S, const Epi& E, const int tid) {
;     ...
;     f32x4 acc[2][2][4][2];
; #pragma unroll
;     for (int a = 0; a < 2; ++a)
; #pragma unroll
;         for (int b = 0; b < 2; ++b)
; #pragma unroll
;             for (int m = 0; m < 4; ++m)
; #pragma unroll
;                 for (int n = 0; n < 2; ++n) acc[a][b][m][n] = (f32x4){0.f, 0.f, 0.f, 0.f};
;     ...
;         const bool has_next = S.next(ui + 1, nxt);
;         const char* nA = has_next ? (const char*)g.A + (size_t)nxt.pm * tstepA : cA; const char* nB = has_next ? (const char*)g.Bt + (size_t)nxt.pn * tstepB : cB;
;         for (int t = 0; t < nt; t += 2) {
;             const bool last = (t == nt - 2);
;             const char* a1 = cA + (size_t)(t + 1) * kstep;
;             const char* a2 = last ? nA : cA + (size_t)(t + 2) * kstep; const char* b2 = last ? nB : cB + (size_t)(t + 2) * kstep;
;             const char* a3 = a2 + kstep; const char* b3 = b2 + kstep;
.LBB0_312:
	s_ashr_i32 s43, s42, 31
	s_lshl_b64 s[24:25], s[42:43], 19
	s_add_u32 s46, s2, s24
	s_addc_u32 s47, s4, s25
	s_and_b64 s[24:25], s[44:45], exec
	s_cselect_b32 s40, s47, s53
	s_cselect_b32 s43, s46, s52
	s_ashr_i32 s39, s38, 31
	s_lshl_b64 s[24:25], s[38:39], 19
	s_add_u32 s48, s16, s24
	s_addc_u32 s49, s17, s25
	s_and_b64 s[24:25], s[44:45], exec
	s_cselect_b32 s39, s49, s51
	s_cselect_b32 s58, s48, s50
	s_add_u32 s59, s50, 0x100
	s_addc_u32 s63, s51, 0
	s_add_u32 s50, s52, 0x40080
	v_mov_b32_e32 v0, 0
	s_addc_u32 s51, s53, 0
	s_mov_b32 s65, -2
	v_mov_b32_e32 v1, v0
	v_mov_b64_e32 v[2:3], 0
	v_mov_b64_e32 v[4:5], 0
	v_mov_b64_e32 v[6:7], 0
	v_mov_b64_e32 v[8:9], 0
	v_mov_b64_e32 v[10:11], 0
	v_mov_b64_e32 v[12:13], 0
	v_mov_b64_e32 v[14:15], 0
	v_mov_b64_e32 v[16:17], 0
	v_mov_b64_e32 v[18:19], 0
	v_mov_b64_e32 v[20:21], 0
	v_mov_b64_e32 v[22:23], 0
	v_mov_b64_e32 v[24:25], 0
	v_mov_b64_e32 v[26:27], 0
	v_mov_b64_e32 v[28:29], 0
	v_mov_b64_e32 v[30:31], 0
	v_mov_b64_e32 v[32:33], 0
	v_mov_b64_e32 v[34:35], 0
	v_mov_b64_e32 v[36:37], 0
	v_mov_b64_e32 v[38:39], 0
	v_mov_b64_e32 v[40:41], 0
	v_mov_b64_e32 v[42:43], 0
	v_mov_b64_e32 v[44:45], 0
	v_mov_b64_e32 v[46:47], 0
	v_mov_b64_e32 v[48:49], 0
	v_mov_b64_e32 v[50:51], 0
	v_mov_b64_e32 v[52:53], 0
	v_mov_b64_e32 v[54:55], 0
	v_mov_b64_e32 v[56:57], 0
	v_mov_b64_e32 v[58:59], 0
	v_mov_b64_e32 v[60:61], 0
	v_mov_b64_e32 v[62:63], 0
	v_mov_b64_e32 v[64:65], 0
	v_mov_b64_e32 v[66:67], 0
	v_mov_b64_e32 v[68:69], 0
	v_mov_b64_e32 v[70:71], 0
	v_mov_b64_e32 v[72:73], 0
	v_mov_b64_e32 v[74:75], 0
	v_mov_b64_e32 v[76:77], 0
	v_mov_b64_e32 v[78:79], 0
	v_mov_b64_e32 v[80:81], 0
	v_mov_b64_e32 v[82:83], 0
	v_mov_b64_e32 v[84:85], 0
	v_mov_b64_e32 v[86:87], 0
	v_mov_b64_e32 v[88:89], 0
	v_mov_b64_e32 v[90:91], 0
	v_mov_b64_e32 v[92:93], 0
	v_mov_b64_e32 v[94:95], 0
	v_mov_b64_e32 v[96:97], 0
	v_mov_b64_e32 v[98:99], 0
	v_mov_b64_e32 v[100:101], 0
	v_mov_b64_e32 v[102:103], 0
	v_mov_b64_e32 v[104:105], 0
	v_mov_b64_e32 v[106:107], 0
	v_mov_b64_e32 v[108:109], 0
	v_mov_b64_e32 v[110:111], 0
	v_mov_b64_e32 v[112:113], 0
	v_mov_b64_e32 v[114:115], 0
	v_mov_b64_e32 v[116:117], 0
	v_mov_b64_e32 v[118:119], 0
	v_mov_b64_e32 v[120:121], 0
	v_mov_b64_e32 v[122:123], 0
	v_mov_b64_e32 v[124:125], 0
	v_mov_b64_e32 v[126:127], 0

; template <class Epi, class Sched, bool ALIGN_EPI = false, bool SP2 = false>
; __device__ __forceinline__ void gemm_phase(PG8_LAS unsigned char* lds, const Gemm g, const Sched& S, const Epi& E, const int tid) {
;     ...
;     f32x4 acc[2][2][4][2];
; #pragma unroll
;     for (int a = 0; a < 2; ++a)
; #pragma unroll
;         for (int b = 0; b < 2; ++b)
; #pragma unroll
;             for (int m = 0; m < 4; ++m)
; #pragma unroll
;                 for (int n = 0; n < 2; ++n) acc[a][b][m][n] = (f32x4){0.f, 0.f, 0.f, 0.f};
;     ...
;         const bool has_next = S.next(ui + 1, nxt);
;         const char* nA = has_next ? (const char*)g.A + (size_t)nxt.pm * tstepA : cA; const char* nB = has_next ? (const char*)g.Bt + (size_t)nxt.pn * tstepB : cB;
;         for (int t = 0; t < nt; t += 2) {
;             const bool last = (t == nt - 2);
;             const char* a1 = cA + (size_t)(t + 1) * kstep;
;             const char* a2 = last ? nA : cA + (size_t)(t + 2) * kstep; const char* b2 = last ? nB : cB + (size_t)(t + 2) * kstep;
;             const char* a3 = a2 + kstep; const char* b3 = b2 + kstep;
.LBB0_346:
	s_add_u32 s20, s48, 0x100
	v_mov_b32_e32 v0, 0
	s_addc_u32 s21, s49, 0
	s_mov_b32 s24, -2
	v_mov_b32_e32 v1, v0
	v_mov_b64_e32 v[2:3], 0
	v_mov_b64_e32 v[4:5], 0
	v_mov_b64_e32 v[6:7], 0
	v_mov_b64_e32 v[16:17], 0
	v_mov_b64_e32 v[18:19], 0
	v_mov_b64_e32 v[20:21], 0
	v_mov_b64_e32 v[22:23], 0
	s_waitcnt vmcnt(0)
	v_mov_b64_e32 v[8:9], 0
	v_mov_b64_e32 v[10:11], 0
	v_mov_b64_e32 v[12:13], 0
	v_mov_b64_e32 v[14:15], 0
	v_mov_b64_e32 v[24:25], 0
	v_mov_b64_e32 v[26:27], 0
	v_mov_b64_e32 v[28:29], 0
	v_mov_b64_e32 v[30:31], 0
	v_mov_b64_e32 v[32:33], 0
	v_mov_b64_e32 v[34:35], 0
	v_mov_b64_e32 v[36:37], 0
	v_mov_b64_e32 v[38:39], 0
	v_mov_b64_e32 v[40:41], 0
	v_mov_b64_e32 v[42:43], 0
	v_mov_b64_e32 v[44:45], 0
	v_mov_b64_e32 v[46:47], 0
	v_mov_b64_e32 v[48:49], 0
	v_mov_b64_e32 v[50:51], 0
	v_mov_b64_e32 v[52:53], 0
	v_mov_b64_e32 v[54:55], 0
	v_mov_b64_e32 v[56:57], 0
	v_mov_b64_e32 v[58:59], 0
	v_mov_b64_e32 v[84:85], 0
	v_mov_b64_e32 v[86:87], 0
	v_mov_b64_e32 v[96:97], 0
	v_mov_b64_e32 v[98:99], 0
	v_mov_b64_e32 v[100:101], 0
	v_mov_b64_e32 v[102:103], 0
	v_mov_b64_e32 v[104:105], 0
	v_mov_b64_e32 v[106:107], 0
	v_mov_b64_e32 v[108:109], 0
	v_mov_b64_e32 v[110:111], 0
	v_mov_b64_e32 v[112:113], 0
	v_mov_b64_e32 v[114:115], 0
	v_mov_b64_e32 v[116:117], 0
	v_mov_b64_e32 v[118:119], 0
	v_mov_b64_e32 v[120:121], 0
	v_mov_b64_e32 v[122:123], 0
	v_mov_b64_e32 v[124:125], 0
	v_mov_b64_e32 v[126:127], 0
	v_mov_b64_e32 v[128:129], 0
	v_mov_b64_e32 v[130:131], 0
	v_mov_b64_e32 v[132:133], 0
	v_mov_b64_e32 v[134:135], 0
	v_mov_b64_e32 v[136:137], 0
	v_mov_b64_e32 v[138:139], 0
	v_mov_b64_e32 v[140:141], 0
	v_mov_b64_e32 v[142:143], 0
	v_mov_b64_e32 v[144:145], 0
	v_mov_b64_e32 v[146:147], 0
	v_mov_b64_e32 v[148:149], 0
	v_mov_b64_e32 v[150:151], 0
	v_mov_b64_e32 v[152:153], 0
	v_mov_b64_e32 v[154:155], 0
	v_mov_b64_e32 v[156:157], 0
	v_mov_b64_e32 v[158:159], 0
